# speedup vs baseline: 1.0579x; 1.0351x over previous
; template <bool SBK>
; __device__ __forceinline__ void attn_item(KP p, int layer, int b, int hh, int qt, char* smem, int tix) {
;     ...
;   bf16x8 qf[4];
;   {
;     const u16* qptr = Rb + (size_t)(rowbase + qpos) * RLD + qcol + hf * 8;
; #pragma unroll
;     for (int ks = 0; ks < 4; ++ks) qf[ks] = *(const bf16x8*)(qptr + ks * 16);
;   }
;   u16* Kb0 = (u16*)smem;
;   u16* Vb0 = (u16*)(smem + 2 * KBUF_B);
;   float* comb = (float*)(smem + 2 * KBUF_B + 2 * VBUF_B);
;   const int srow = tid >> 3, sch = tid & 7;
;   const int kt_hi = 2 * qt + 1;
;   const int ntile = kt_hi;
;   uint4 kr0, kr1, vr0, vr1;
;   auto gload = [&](int kt) {
;     const u16* kp = Rb + (size_t)(rowbase + kt * 64 + srow) * RLD + kcol0 + sch * 8;
;     kr0 = *(const uint4*)kp; kr1 = *(const uint4*)(kp + 64);
;     const u16* vp = Tb + ((size_t)(trow0 + srow) * 2 + b) * LP + kt * 64 + sch * 8;
;     vr0 = *(const uint4*)vp; vr1 = *(const uint4*)(vp + (size_t)64 * 2 * LP);
;   };
;   auto lwrite = [&](int buf) {
;     u16* kb = Kb0 + buf * (KBUF_B / 2);
;     *(uint4*)(kb + srow * KST + sch * 8) = kr0;
;     *(uint4*)(kb + srow * KST + 64 + sch * 8) = kr1;
;     u16* vb = Vb0 + buf * (VBUF_B / 2);
;     *(uint2*)(vb + srow * VST + sch * 8) = make_uint2(vr0.x, vr0.y);
;     *(uint2*)(vb + srow * VST + sch * 8 + 4) = make_uint2(vr0.z, vr0.w);
;     *(uint2*)(vb + (srow + 64) * VST + sch * 8) = make_uint2(vr1.x, vr1.y);
;     *(uint2*)(vb + (srow + 64) * VST + sch * 8 + 4) = make_uint2(vr1.z, vr1.w);
;   };
;   f32x16 O[NDV];
; #pragma unroll
;   for (int i = 0; i < NDV; ++i)
; #pragma unroll
;     for (int r = 0; r < 16; ++r) O[i][r] = 0.f;
;   float m_run = -1e30f, l_run = 0.f, Rsum = 0.f;
;   bool sb_done = false;
;   const float sc2 = 0.125f * 1.4426950408889634f;
;   __syncthreads();
;   gload(SBK ? kt_hi : 1);
;   lwrite(0);
;   __syncthreads();
;     ...
;     if (i + 1 < ntile) lwrite((i + 1) & 1);
;     __syncthreads();
;   }
.LBB0_362:
	v_ashrrev_i32_e32 v8, 3, v3
	v_readlane_b32 s4, v245, 45
	v_ashrrev_i32_e32 v85, 1, v0
	v_and_b32_e32 v0, 1, v0
	v_add_u32_e32 v140, s4, v8
	s_movk_i32 s4, 0x110
	v_bfe_u32 v5, v28, 5, 1
	v_lshlrev_b32_e32 v2, 4, v28
	v_mul_lo_u32 v7, v8, s4
	s_movk_i32 s4, 0x88
	v_sub_u32_e32 v84, 64, v85
	v_cmp_eq_u32_e32 vcc, 1, v0
	v_and_b32_e32 v139, 31, v28
	v_lshlrev_b32_e32 v4, 3, v5
	v_lshlrev_b32_e32 v0, 4, v5
	v_and_b32_e32 v2, 0x70, v2
	v_mul_lo_u32 v6, v8, s4
	v_lshlrev_b32_e32 v134, 2, v5
	s_and_saveexec_b64 s[4:5], vcc
	s_xor_b64 s[58:59], exec, s[4:5]
	s_cbranch_execz .LBB0_374
	v_readfirstlane_b32 s4, v3
	s_and_b32 s6, s4, 64
	s_ashr_i32 s4, s4, 2
	v_lshlrev_b32_e32 v102, 7, v84
	s_andn2_b32 s4, s4, 31
	v_add_u32_e32 v3, s4, v102
	v_readlane_b32 s0, v245, 43
	v_or_b32_e32 v100, v3, v139
	s_or_b32 s55, s6, s0
	v_readlane_b32 s0, v245, 45
	s_lshl_b32 s48, s55, 1
	v_lshlrev_b32_e32 v133, 1, v84
	v_add_u32_e32 v98, s0, v100
	v_ashrrev_i32_e32 v99, 31, v98
	v_lshlrev_b64 v[10:11], 13, v[98:99]
	v_lshl_add_u64 v[10:11], s[50:51], 0, v[10:11]
	v_lshl_add_u64 v[10:11], v[10:11], 0, s[48:49]
	v_lshl_add_u64 v[10:11], v[10:11], 0, v[0:1]
	v_or_b32_e32 v159, 1, v133
	global_load_dwordx4 v[66:69], v[10:11], off offset:2048
	global_load_dwordx4 v[70:73], v[10:11], off offset:2080
	global_load_dwordx4 v[74:77], v[10:11], off offset:2112
	global_load_dwordx4 v[78:81], v[10:11], off offset:2144
	v_lshl_add_u32 v10, v159, 6, v140
	v_ashrrev_i32_e32 v11, 31, v10
	v_readlane_b32 s8, v244, 45
	v_lshlrev_b64 v[10:11], 13, v[10:11]
	v_readlane_b32 s9, v244, 46
	v_or_b32_e32 v141, 31, v3
	v_mov_b32_e32 v3, v1
	v_lshl_add_u64 v[10:11], s[8:9], 0, v[10:11]
	v_readlane_b32 s0, v245, 44
	v_lshl_add_u64 v[10:11], v[10:11], 0, v[2:3]
	s_nop 0
	v_add_u32_e32 v8, s0, v8
	v_readlane_b32 s0, v245, 42
	s_barrier
	global_load_dwordx4 v[82:85], v[10:11], off offset:3072
	global_load_dwordx4 v[86:89], v[10:11], off offset:3200
	v_lshl_or_b32 v10, v8, 1, s0
	v_mov_b64_e32 v[8:9], s[70:71]
	s_movk_i32 s0, 0x4100
	v_mad_i64_i32 v[8:9], s[4:5], v10, s0, v[8:9]
	v_lshlrev_b32_e32 v10, 7, v159
	v_mov_b32_e32 v11, v1
	v_lshl_add_u64 v[10:11], v[8:9], 0, v[10:11]
	v_lshl_add_u64 v[10:11], v[10:11], 0, v[2:3]
	s_mov_b32 s0, 0x208000
	global_load_dwordx4 v[90:93], v[10:11], off
	v_add_co_u32_e32 v10, vcc, s0, v10
	v_add3_u32 v161, 0, v6, v2
	s_nop 0
	v_addc_co_u32_e32 v11, vcc, 0, v11, vcc
	global_load_dwordx4 v[94:97], v[10:11], off
	s_lshl_b32 s4, s6, 1
	v_add3_u32 v160, 0, v7, v2
	v_add_u32_e32 v6, 0x8800, v161
	v_lshl_add_u64 v[104:105], s[8:9], 0, v[2:3]
	v_lshl_add_u64 v[106:107], v[8:9], 0, v[2:3]
	s_add_i32 s7, s4, 0
	v_or_b32_e32 v2, s6, v139
	v_mul_u32_u24_e32 v3, 0x110, v139
	v_add3_u32 v162, s7, v0, v3
	v_mul_u32_u24_e32 v0, 0x88, v2
	v_mov_b32_e32 v14, v1
	v_mov_b32_e32 v15, v1
	v_cmp_eq_u32_e64 s[4:5], 0, v5
	v_add3_u32 v163, 0, v4, v0
	v_mov_b32_e32 v0, v1
	v_mov_b32_e32 v2, v1
	v_mov_b32_e32 v3, v1
	v_mov_b32_e32 v4, v1
	v_mov_b32_e32 v5, v1
	v_mov_b32_e32 v7, v1
	v_mov_b32_e32 v8, v1
	v_mov_b32_e32 v9, v1
	v_mov_b32_e32 v10, v1
	v_mov_b32_e32 v11, v1
	v_mov_b32_e32 v12, v1
	v_mov_b32_e32 v13, v1
	s_mov_b32 s48, 0
	v_mov_b32_e32 v101, v100
	s_mov_b64 s[94:95], 0
	v_mov_b32_e32 v109, 0
	s_mov_b64 s[82:83], 0
	s_waitcnt vmcnt(3)
	ds_write_b128 v160, v[82:85]
	s_waitcnt vmcnt(2)
	ds_write_b128 v160, v[86:89] offset:128
	s_waitcnt vmcnt(1)
	ds_write2_b64 v6, v[90:91], v[92:93] offset1:1
	v_add_u32_e32 v6, 0xaa00, v161
	s_waitcnt vmcnt(0)
	ds_write2_b64 v6, v[94:95], v[96:97] offset1:1
	v_mov_b32_e32 v6, v1
	v_mov_b64_e32 v[32:33], v[14:15]
	v_mov_b64_e32 v[30:31], v[12:13]
	v_mov_b64_e32 v[28:29], v[10:11]
	v_mov_b64_e32 v[26:27], v[8:9]
	v_mov_b64_e32 v[24:25], v[6:7]
	v_mov_b64_e32 v[22:23], v[4:5]
	v_mov_b64_e32 v[20:21], v[2:3]
	v_mov_b64_e32 v[18:19], v[0:1]
	v_mov_b64_e32 v[16:17], v[14:15]
	v_mov_b64_e32 v[14:15], v[12:13]
	v_mov_b64_e32 v[12:13], v[10:11]
	v_mov_b64_e32 v[10:11], v[8:9]
	v_mov_b64_e32 v[8:9], v[6:7]
	v_mov_b64_e32 v[6:7], v[4:5]
	v_mov_b64_e32 v[4:5], v[2:3]
	v_mov_b64_e32 v[2:3], v[0:1]
	v_mov_b32_e32 v239, 0x22000
	v_mov_b32_e32 v238, 0x22004
	v_mov_b32_e32 v237, 0x22008
	v_mov_b32_e32 v241, 1
	ds_write_b32 v239, v1
	ds_write_b32 v238, v1
	ds_write_b32 v237, v1
	s_waitcnt lgkmcnt(0)
	s_barrier
	s_branch .LBB0_365
.LBB0_364:
	s_or_b64 exec, exec, s[8:9]
	v_cmp_eq_u32_e32 vcc, s48, v159
	s_or_b64 s[82:83], vcc, s[82:83]
	v_subrev_u32_e32 v102, 64, v102
	s_mov_b64 s[10:11], exec
	s_mov_b64 exec, 1
	ds_write_b32 v238, v1
	s_cmp_eq_u64 s[94:95], 0
	s_cbranch_scc1 .Lsbk_nopub
	ds_add_u32 v239, v241
.Lsbk_nopub:
	s_mov_b64 exec, s[10:11]
	s_waitcnt lgkmcnt(0)
	s_barrier
	ds_read_b32 v236, v239
	v_mov_b32_e32 v240, v239
	v_mov_b32_e32 v239, v238
	v_mov_b32_e32 v238, v237
	v_mov_b32_e32 v237, v240
	s_waitcnt lgkmcnt(0)
	v_readfirstlane_b32 s10, v236
	s_cmp_eq_u32 s10, 8
	s_cbranch_scc1 .LBB0_371
	s_andn2_b64 exec, exec, s[82:83]
	s_cbranch_execz .LBB0_371

; #define MFMA_FENCE() do { __builtin_amdgcn_sched_barrier(0); asm volatile("s_nop 15\n\ts_nop 15" ::: "memory"); __builtin_amdgcn_sched_barrier(0); } while (0)
; DEVI f32x16 mfma32(bf16x8 a, bf16x8 b, f32x16 c) { return __builtin_amdgcn_mfma_f32_32x32x16_bf16(a, b, c, 0, 0, 0); }
; template <bool SBK>
; __device__ __forceinline__ void attn_item(KP p, int layer, int b, int hh, int qt, char* smem, int tix) {
;     ...
;     if (kt * 64 <= qmax_w && !sb_done) {
;       f32x16 s[2];
;       __builtin_amdgcn_s_setprio(1);
; #pragma unroll
;       for (int kb2 = 0; kb2 < 2; ++kb2) {
; #pragma unroll
;         for (int r = 0; r < 16; ++r) s[kb2][r] = 0.f;
; #pragma unroll
;         for (int ks = 0; ks < 4; ++ks) {
;           bf16x8 a = *(const bf16x8*)(kb + (kb2 * 32 + l32) * KST + c * 64 + ks * 16 + hf * 8);
;           s[kb2] = mfma32(a, qf[ks], s[kb2]);
;         }
;       }
;       __builtin_amdgcn_s_setprio(0);
;       bf16x8 pf[2][2];
;       MFMA_FENCE();
;     ...
;       for (int d = 0; d < NDV; ++d) {
;         const int vrow = (SBK ? c * 64 : 0) + d * 32 + l32;
; #pragma unroll
;         for (int kb2 = 0; kb2 < 2; ++kb2)
; #pragma unroll
;           for (int s2 = 0; s2 < 2; ++s2) {
;             const u16* vp = vb + vrow * VST + kb2 * 32 + 16 * s2 + 4 * hf;
;             bf16x4 lo = *(const bf16x4*)vp, hi = *(const bf16x4*)(vp + 8);
;             bf16x8 a = __builtin_shufflevector(lo, hi, 0, 1, 2, 3, 4, 5, 6, 7);
;             O[d] = mfma32(a, pf[kb2][s2], O[d]);
.LBB0_389:
	s_or_b64 exec, exec, s[6:7]
	s_sub_i32 s6, s14, 64
	v_cmp_le_i32_e32 vcc, s6, v141
	s_and_saveexec_b64 s[18:19], vcc
	s_cbranch_execz .LBB0_393
	s_bitcmp1_b32 s8, 0
	s_setprio 1
	s_cselect_b32 s7, 0x2200, 0
	s_lshl_b32 s15, s7, 1
	v_add3_u32 v161, v151, s15, v157
	ds_read_b128 v[194:197], v161
	ds_read_b128 v[198:201], v161 offset:32
	ds_read_b128 v[202:205], v161 offset:64
	ds_read_b128 v[206:209], v161 offset:96
	ds_read_b128 v[210:213], v161 offset:8704
	ds_read_b128 v[214:217], v161 offset:8736
	ds_read_b128 v[218:221], v161 offset:8768
	ds_read_b128 v[222:225], v161 offset:8800
	s_waitcnt lgkmcnt(7)
	v_mfma_f32_32x32x16_bf16 v[82:97], v[194:197], v[98:101], 0
	s_waitcnt lgkmcnt(6)
	v_mfma_f32_32x32x16_bf16 v[82:97], v[198:201], v[102:105], v[82:97]
	s_waitcnt lgkmcnt(5)
	v_mfma_f32_32x32x16_bf16 v[82:97], v[202:205], v[106:109], v[82:97]
	s_waitcnt lgkmcnt(4)
	v_mfma_f32_32x32x16_bf16 v[82:97], v[206:209], v[110:113], v[82:97]
	s_waitcnt lgkmcnt(3)
	v_mfma_f32_32x32x16_bf16 v[66:81], v[210:213], v[98:101], 0
	s_waitcnt lgkmcnt(2)
	v_mfma_f32_32x32x16_bf16 v[66:81], v[214:217], v[102:105], v[66:81]
	s_waitcnt lgkmcnt(1)
	v_mfma_f32_32x32x16_bf16 v[66:81], v[218:221], v[106:109], v[66:81]
	s_waitcnt lgkmcnt(0)
	v_mfma_f32_32x32x16_bf16 v[66:81], v[222:225], v[110:113], v[66:81]
	s_setprio 0
	v_add3_u32 v242, v152, s15, v159
	v_add_u32_e32 v243, 0x8800, v242
	ds_read2_b64 v[194:197], v243 offset1:2
	ds_read2_b64 v[198:201], v243 offset0:4 offset1:6
	ds_read2_b64 v[202:205], v243 offset0:8 offset1:10
	ds_read2_b64 v[206:209], v243 offset0:12 offset1:14
	v_add_u32_e32 v243, 0x9800, v242
	ds_read2_b64 v[210:213], v243 offset0:32 offset1:34
	ds_read2_b64 v[214:217], v243 offset0:36 offset1:38
	ds_read2_b64 v[218:221], v243 offset0:40 offset1:42
	ds_read2_b64 v[222:225], v243 offset0:44 offset1:46
	v_add_u32_e32 v243, 0xa800, v242
	ds_read2_b64 v[226:229], v243 offset0:64 offset1:66
	ds_read2_b64 v[230:233], v243 offset0:68 offset1:70
	ds_read2_b64 v[234:237], v243 offset0:72 offset1:74
	ds_read2_b64 v[238:241], v243 offset0:76 offset1:78
	s_nop 3
	s_add_i32 s7, s14, -1
	v_add_u32_e32 v161, s14, v134
	v_subrev_u32_e32 v162, 64, v161
	s_cmpk_lt_u32 s6, 0x70
	v_cmp_gt_i32_e32 vcc, s7, v148
	s_cbranch_vccz .Ldiff_fast
	s_cselect_b64 s[8:9], -1, 0
	v_cmp_gt_i32_e64 s[6:7], v162, v133
	s_or_b64 s[6:7], s[8:9], s[6:7]
	v_mul_f32_e32 v82, 0x3e38aa3b, v82
	s_and_b64 s[6:7], vcc, s[6:7]
	v_cndmask_b32_e64 v82, v82, v182, s[6:7]
	v_cmp_ge_i32_e64 s[6:7], v162, v133
	s_or_b64 s[6:7], s[8:9], s[6:7]
	v_mul_f32_e32 v83, 0x3e38aa3b, v83
	s_and_b64 s[6:7], vcc, s[6:7]
	v_subrev_u32_e32 v163, 62, v161
	v_cndmask_b32_e64 v83, v83, v182, s[6:7]
	v_cmp_gt_i32_e64 s[6:7], v163, v133
	s_or_b64 s[6:7], s[8:9], s[6:7]
	v_mul_f32_e32 v84, 0x3e38aa3b, v84
	s_and_b64 s[6:7], vcc, s[6:7]
	v_subrev_u32_e32 v163, 61, v161
	v_cndmask_b32_e64 v84, v84, v182, s[6:7]
	v_cmp_gt_i32_e64 s[6:7], v163, v133
	s_or_b64 s[6:7], s[8:9], s[6:7]
	v_mul_f32_e32 v85, 0x3e38aa3b, v85
	s_and_b64 s[6:7], vcc, s[6:7]
	v_subrev_u32_e32 v163, 56, v161
	v_cndmask_b32_e64 v85, v85, v182, s[6:7]
	v_cmp_gt_i32_e64 s[6:7], v163, v133
	s_or_b64 s[6:7], s[8:9], s[6:7]
	v_mul_f32_e32 v86, 0x3e38aa3b, v86
	s_and_b64 s[6:7], vcc, s[6:7]
	v_subrev_u32_e32 v163, 55, v161
	v_cndmask_b32_e64 v86, v86, v182, s[6:7]
	v_cmp_gt_i32_e64 s[6:7], v163, v133
	s_or_b64 s[6:7], s[8:9], s[6:7]
	v_mul_f32_e32 v87, 0x3e38aa3b, v87
	s_and_b64 s[6:7], vcc, s[6:7]
	v_subrev_u32_e32 v163, 54, v161
	v_cndmask_b32_e64 v87, v87, v182, s[6:7]
	v_cmp_gt_i32_e64 s[6:7], v163, v133
	s_or_b64 s[6:7], s[8:9], s[6:7]
	v_mul_f32_e32 v88, 0x3e38aa3b, v88
	s_and_b64 s[6:7], vcc, s[6:7]
	v_subrev_u32_e32 v163, 53, v161
	v_cndmask_b32_e64 v88, v88, v182, s[6:7]
	v_cmp_gt_i32_e64 s[6:7], v163, v133
	s_or_b64 s[6:7], s[8:9], s[6:7]
	v_mul_f32_e32 v89, 0x3e38aa3b, v89
	s_and_b64 s[6:7], vcc, s[6:7]
	v_subrev_u32_e32 v163, 48, v161
	v_cndmask_b32_e64 v89, v89, v182, s[6:7]
	v_cmp_gt_u32_e64 s[6:7], s53, v163
	v_cmp_gt_i32_e64 s[8:9], v163, v133
	s_or_b64 s[6:7], s[6:7], s[8:9]
	v_mul_f32_e32 v90, 0x3e38aa3b, v90
	s_and_b64 s[6:7], vcc, s[6:7]
	v_subrev_u32_e32 v163, 47, v161
	v_cndmask_b32_e64 v90, v90, v182, s[6:7]
	v_cmp_gt_u32_e64 s[6:7], s53, v163
	v_cmp_gt_i32_e64 s[8:9], v163, v133
	s_or_b64 s[6:7], s[6:7], s[8:9]
	v_mul_f32_e32 v91, 0x3e38aa3b, v91
	s_and_b64 s[6:7], vcc, s[6:7]
	v_subrev_u32_e32 v163, 46, v161
	v_cndmask_b32_e64 v91, v91, v182, s[6:7]
	v_cmp_gt_u32_e64 s[6:7], s53, v163
	v_cmp_gt_i32_e64 s[8:9], v163, v133
	s_or_b64 s[6:7], s[6:7], s[8:9]
	v_mul_f32_e32 v92, 0x3e38aa3b, v92
	s_and_b64 s[6:7], vcc, s[6:7]
	v_subrev_u32_e32 v163, 45, v161
	v_cndmask_b32_e64 v92, v92, v182, s[6:7]
	v_cmp_gt_u32_e64 s[6:7], s53, v163
	v_cmp_gt_i32_e64 s[8:9], v163, v133
	s_or_b64 s[6:7], s[6:7], s[8:9]
	v_mul_f32_e32 v93, 0x3e38aa3b, v93
	s_and_b64 s[6:7], vcc, s[6:7]
	v_subrev_u32_e32 v163, 40, v161
	v_cndmask_b32_e64 v93, v93, v182, s[6:7]
	v_cmp_gt_u32_e64 s[6:7], s53, v163
	v_cmp_gt_i32_e64 s[8:9], v163, v133
	s_or_b64 s[6:7], s[6:7], s[8:9]
	v_mul_f32_e32 v94, 0x3e38aa3b, v94
	s_and_b64 s[6:7], vcc, s[6:7]
	v_subrev_u32_e32 v163, 39, v161
	v_cndmask_b32_e64 v94, v94, v182, s[6:7]
; DEVI float max32x(float v) { float a, b; swap32(v, a, b); return fmaxf(a, b); }
; template <bool SBK>
; __device__ __forceinline__ void attn_item(KP p, int layer, int b, int hh, int qt, char* smem, int tix) {
;     ...
;         float mx = -1e30f;
; #pragma unroll
;         for (int kb2 = 0; kb2 < 2; ++kb2)
; #pragma unroll
;           for (int r = 0; r < 16; ++r) {
;             float t = s[kb2][r] * sc2;
;             if (need_mask) {
;               int kp = kt * 64 + kb2 * 32 + 8 * (r >> 2) + 4 * hf + (r & 3);
;               if (kp < PADF || kp > qpos) t = -1e30f;
;             }
;             s[kb2][r] = t;
;             mx = fmaxf(mx, t);
;           }
;         mx = max32x(mx);
	v_cmp_gt_u32_e64 s[6:7], s53, v163
	v_cmp_gt_i32_e64 s[8:9], v163, v133
	s_or_b64 s[6:7], s[6:7], s[8:9]
	v_mul_f32_e32 v95, 0x3e38aa3b, v95
	s_and_b64 s[6:7], vcc, s[6:7]
	v_subrev_u32_e32 v163, 38, v161
	v_cndmask_b32_e64 v95, v95, v182, s[6:7]
	v_cmp_gt_u32_e64 s[6:7], s53, v163
	v_cmp_gt_i32_e64 s[8:9], v163, v133
	s_or_b64 s[6:7], s[6:7], s[8:9]
	v_mul_f32_e32 v96, 0x3e38aa3b, v96
	s_and_b64 s[6:7], vcc, s[6:7]
	v_subrev_u32_e32 v163, 37, v161
	v_cndmask_b32_e64 v96, v96, v182, s[6:7]
	v_cmp_gt_u32_e64 s[6:7], s53, v163
	v_cmp_gt_i32_e64 s[8:9], v163, v133
	s_or_b64 s[6:7], s[6:7], s[8:9]
	v_mul_f32_e32 v97, 0x3e38aa3b, v97
	s_and_b64 s[6:7], vcc, s[6:7]
	v_subrev_u32_e32 v163, 32, v161
	v_cndmask_b32_e64 v97, v97, v182, s[6:7]
	v_cmp_gt_u32_e64 s[6:7], s53, v163
	v_cmp_gt_i32_e64 s[8:9], v163, v133
	s_or_b64 s[6:7], s[6:7], s[8:9]
	v_mul_f32_e32 v66, 0x3e38aa3b, v66
	s_and_b64 s[6:7], vcc, s[6:7]
	v_subrev_u32_e32 v163, 31, v161
	v_cndmask_b32_e64 v66, v66, v182, s[6:7]
	v_cmp_gt_u32_e64 s[6:7], s53, v163
	v_cmp_gt_i32_e64 s[8:9], v163, v133
	s_or_b64 s[6:7], s[6:7], s[8:9]
	v_mul_f32_e32 v67, 0x3e38aa3b, v67
	s_and_b64 s[6:7], vcc, s[6:7]
	v_subrev_u32_e32 v163, 30, v161
	v_cndmask_b32_e64 v67, v67, v182, s[6:7]
	v_cmp_gt_u32_e64 s[6:7], s53, v163
	v_cmp_gt_i32_e64 s[8:9], v163, v133
	s_or_b64 s[6:7], s[6:7], s[8:9]
	v_mul_f32_e32 v68, 0x3e38aa3b, v68
	s_and_b64 s[6:7], vcc, s[6:7]
	v_subrev_u32_e32 v163, 29, v161
	v_cndmask_b32_e64 v68, v68, v182, s[6:7]
	v_cmp_gt_u32_e64 s[6:7], s53, v163
	v_cmp_gt_i32_e64 s[8:9], v163, v133
	s_or_b64 s[6:7], s[6:7], s[8:9]
	v_mul_f32_e32 v69, 0x3e38aa3b, v69
	s_and_b64 s[6:7], vcc, s[6:7]
	v_subrev_u32_e32 v163, 24, v161
	v_cndmask_b32_e64 v69, v69, v182, s[6:7]
	v_cmp_gt_u32_e64 s[6:7], s53, v163
	v_cmp_gt_i32_e64 s[8:9], v163, v133
	s_or_b64 s[6:7], s[6:7], s[8:9]
	v_mul_f32_e32 v70, 0x3e38aa3b, v70
	s_and_b64 s[6:7], vcc, s[6:7]
	v_subrev_u32_e32 v163, 23, v161
	v_cndmask_b32_e64 v70, v70, v182, s[6:7]
	v_cmp_gt_u32_e64 s[6:7], s53, v163
	v_cmp_gt_i32_e64 s[8:9], v163, v133
	s_or_b64 s[6:7], s[6:7], s[8:9]
	v_mul_f32_e32 v71, 0x3e38aa3b, v71
	s_and_b64 s[6:7], vcc, s[6:7]
	v_subrev_u32_e32 v163, 22, v161
	v_cndmask_b32_e64 v71, v71, v182, s[6:7]
	v_cmp_gt_u32_e64 s[6:7], s53, v163
	v_cmp_gt_i32_e64 s[8:9], v163, v133
	s_or_b64 s[6:7], s[6:7], s[8:9]
	v_mul_f32_e32 v72, 0x3e38aa3b, v72
	s_and_b64 s[6:7], vcc, s[6:7]
	v_subrev_u32_e32 v163, 21, v161
	v_cndmask_b32_e64 v72, v72, v182, s[6:7]
	v_cmp_gt_u32_e64 s[6:7], s53, v163
	v_cmp_gt_i32_e64 s[8:9], v163, v133
	s_or_b64 s[6:7], s[6:7], s[8:9]
	v_mul_f32_e32 v73, 0x3e38aa3b, v73
	s_and_b64 s[6:7], vcc, s[6:7]
	v_add_u32_e32 v163, -16, v161
	v_cndmask_b32_e64 v73, v73, v182, s[6:7]
	v_cmp_gt_u32_e64 s[6:7], s53, v163
	v_cmp_gt_i32_e64 s[8:9], v163, v133
	s_or_b64 s[6:7], s[6:7], s[8:9]
	v_mul_f32_e32 v74, 0x3e38aa3b, v74
	s_and_b64 s[6:7], vcc, s[6:7]
	v_add_u32_e32 v163, -15, v161
	v_cndmask_b32_e64 v74, v74, v182, s[6:7]
	v_cmp_gt_u32_e64 s[6:7], s53, v163
	v_cmp_gt_i32_e64 s[8:9], v163, v133
	s_or_b64 s[6:7], s[6:7], s[8:9]
	v_mul_f32_e32 v75, 0x3e38aa3b, v75
	s_and_b64 s[6:7], vcc, s[6:7]
	v_add_u32_e32 v163, -14, v161
	v_cndmask_b32_e64 v75, v75, v182, s[6:7]
	v_cmp_gt_u32_e64 s[6:7], s53, v163
	v_cmp_gt_i32_e64 s[8:9], v163, v133
	s_or_b64 s[6:7], s[6:7], s[8:9]
	v_mul_f32_e32 v76, 0x3e38aa3b, v76
	s_and_b64 s[6:7], vcc, s[6:7]
	v_add_u32_e32 v163, -13, v161
	v_cndmask_b32_e64 v76, v76, v182, s[6:7]
	v_cmp_gt_u32_e64 s[6:7], s53, v163
	v_cmp_gt_i32_e64 s[8:9], v163, v133
	v_max3_f32 v162, v82, s23, v83
	s_or_b64 s[6:7], s[6:7], s[8:9]
	v_max3_f32 v162, v162, v84, v85
	v_mul_f32_e32 v77, 0x3e38aa3b, v77
	s_and_b64 s[6:7], vcc, s[6:7]
	v_add_u32_e32 v163, -8, v161
	v_max3_f32 v162, v162, v86, v87
	v_cndmask_b32_e64 v77, v77, v182, s[6:7]
	v_cmp_gt_u32_e64 s[6:7], s53, v163
	v_cmp_gt_i32_e64 s[8:9], v163, v133
	v_max3_f32 v162, v162, v88, v89
	s_or_b64 s[6:7], s[6:7], s[8:9]
	v_max3_f32 v162, v162, v90, v91
	v_mul_f32_e32 v78, 0x3e38aa3b, v78
	s_and_b64 s[6:7], vcc, s[6:7]
	v_add_u32_e32 v163, -7, v161
	v_max3_f32 v162, v162, v92, v93
	v_cndmask_b32_e64 v78, v78, v182, s[6:7]
	v_cmp_gt_u32_e64 s[6:7], s53, v163
	v_cmp_gt_i32_e64 s[8:9], v163, v133
	v_max3_f32 v162, v162, v94, v95
	s_or_b64 s[6:7], s[6:7], s[8:9]
	v_max3_f32 v162, v162, v96, v97
	v_mul_f32_e32 v79, 0x3e38aa3b, v79
	s_and_b64 s[6:7], vcc, s[6:7]
	v_add_u32_e32 v163, -6, v161
	v_max3_f32 v162, v162, v66, v67
	v_cndmask_b32_e64 v79, v79, v182, s[6:7]
	v_cmp_gt_u32_e64 s[6:7], s53, v163
	v_cmp_gt_i32_e64 s[8:9], v163, v133
	v_max3_f32 v162, v162, v68, v69
	s_or_b64 s[6:7], s[6:7], s[8:9]
	v_max3_f32 v162, v162, v70, v71
	v_mul_f32_e32 v80, 0x3e38aa3b, v80
	s_and_b64 s[6:7], vcc, s[6:7]
	v_add_u32_e32 v161, -5, v161
	v_max3_f32 v162, v162, v72, v73
	v_cndmask_b32_e64 v80, v80, v182, s[6:7]
	v_cmp_gt_u32_e64 s[6:7], s53, v161
	v_cmp_gt_i32_e64 s[8:9], v161, v133
	v_max3_f32 v162, v162, v74, v75
	s_or_b64 s[6:7], s[6:7], s[8:9]
	v_max3_f32 v162, v162, v76, v77
	v_mul_f32_e32 v81, 0x3e38aa3b, v81
	s_and_b64 vcc, vcc, s[6:7]
	v_max3_f32 v162, v162, v78, v79
	v_cndmask_b32_e32 v81, v81, v182, vcc
	v_max3_f32 v161, v162, v80, v81

; DEVI f32x16 mfma32(bf16x8 a, bf16x8 b, f32x16 c) { return __builtin_amdgcn_mfma_f32_32x32x16_bf16(a, b, c, 0, 0, 0); }
; template <bool SBK>
; __device__ __forceinline__ void attn_item(KP p, int layer, int b, int hh, int qt, char* smem, int tix) {
;     ...
;         float ps = 0.f;
; #pragma unroll
;         for (int kb2 = 0; kb2 < 2; ++kb2)
; #pragma unroll
;           for (int r = 0; r < 16; ++r) { float e = __builtin_amdgcn_exp2f(s[kb2][r] - m_run); s[kb2][r] = e; ps += e; }
;         l_run += ps;
;     ...
; #pragma unroll
;       for (int kb2 = 0; kb2 < 2; ++kb2)
; #pragma unroll
;         for (int s2 = 0; s2 < 2; ++s2) {
;           float tmp[8];
; #pragma unroll
;           for (int e = 0; e < 8; ++e) tmp[e] = s[kb2][8 * s2 + e];
;           pf[kb2][s2] = pack8(tmp);
;         }
;       asm volatile("s_nop 4" ::: "memory");
;       __builtin_amdgcn_s_setprio(1);
; #pragma unroll
;       for (int d = 0; d < NDV; ++d) {
;         const int vrow = (SBK ? c * 64 : 0) + d * 32 + l32;
; #pragma unroll
;         for (int kb2 = 0; kb2 < 2; ++kb2)
; #pragma unroll
;           for (int s2 = 0; s2 < 2; ++s2) {
;             const u16* vp = vb + vrow * VST + kb2 * 32 + 16 * s2 + 4 * hf;
;             bf16x4 lo = *(const bf16x4*)vp, hi = *(const bf16x4*)(vp + 8);
;             bf16x8 a = __builtin_shufflevector(lo, hi, 0, 1, 2, 3, 4, 5, 6, 7);
;             O[d] = mfma32(a, pf[kb2][s2], O[d]);
;           }
;       }
.LBB0_392:
	v_sub_f32_e32 v82, v82, v155
	v_exp_f32_e32 v82, v82
	v_sub_f32_e32 v83, v83, v155
	v_exp_f32_e32 v83, v83
	v_sub_f32_e32 v84, v84, v155
	v_exp_f32_e32 v84, v84
	v_sub_f32_e32 v85, v85, v155
	v_exp_f32_e32 v85, v85
	v_sub_f32_e32 v86, v86, v155
	v_add_f32_e32 v161, 0, v82
	v_exp_f32_e32 v86, v86
	v_sub_f32_e32 v87, v87, v155
	v_sub_f32_e32 v66, v66, v155
	v_add_f32_e32 v161, v83, v161
	v_exp_f32_e32 v87, v87
	v_sub_f32_e32 v88, v88, v155
	v_exp_f32_e32 v162, v66
	v_sub_f32_e32 v66, v67, v155
	v_add_f32_e32 v161, v84, v161
	v_exp_f32_e32 v88, v88
	v_sub_f32_e32 v89, v89, v155
	v_exp_f32_e32 v163, v66
	v_sub_f32_e32 v66, v68, v155
	v_add_f32_e32 v161, v85, v161
	v_exp_f32_e32 v89, v89
	v_sub_f32_e32 v90, v90, v155
	v_exp_f32_e32 v164, v66
	v_sub_f32_e32 v66, v69, v155
	v_add_f32_e32 v161, v86, v161
	v_exp_f32_e32 v90, v90
	v_sub_f32_e32 v91, v91, v155
	v_exp_f32_e32 v165, v66
	v_sub_f32_e32 v66, v70, v155
	v_add_f32_e32 v161, v87, v161
	v_exp_f32_e32 v91, v91
	v_sub_f32_e32 v92, v92, v155
	v_exp_f32_e32 v166, v66
	v_sub_f32_e32 v66, v71, v155
	v_add_f32_e32 v161, v88, v161
	v_exp_f32_e32 v92, v92
	v_sub_f32_e32 v93, v93, v155
	v_exp_f32_e32 v167, v66
	v_sub_f32_e32 v66, v72, v155
	v_add_f32_e32 v161, v89, v161
	v_exp_f32_e32 v93, v93
	v_sub_f32_e32 v94, v94, v155
	v_exp_f32_e32 v183, v66
	v_sub_f32_e32 v66, v73, v155
	v_add_f32_e32 v161, v90, v161
	v_exp_f32_e32 v94, v94
	v_sub_f32_e32 v95, v95, v155
	v_exp_f32_e32 v184, v66
	v_sub_f32_e32 v66, v74, v155
	v_add_f32_e32 v161, v91, v161
	v_exp_f32_e32 v95, v95
	v_sub_f32_e32 v96, v96, v155
	v_exp_f32_e32 v185, v66
	v_sub_f32_e32 v66, v75, v155
	v_add_f32_e32 v161, v92, v161
	v_exp_f32_e32 v96, v96
	v_sub_f32_e32 v97, v97, v155
	v_exp_f32_e32 v186, v66
	v_sub_f32_e32 v66, v76, v155
	v_add_f32_e32 v161, v93, v161
	v_exp_f32_e32 v97, v97
	v_exp_f32_e32 v187, v66
	v_sub_f32_e32 v66, v77, v155
	v_add_f32_e32 v161, v94, v161
	v_exp_f32_e32 v188, v66
	v_sub_f32_e32 v66, v78, v155
	v_add_f32_e32 v161, v95, v161
	v_exp_f32_e32 v189, v66
	v_sub_f32_e32 v66, v79, v155
	v_add_f32_e32 v161, v96, v161
	v_exp_f32_e32 v190, v66
	v_sub_f32_e32 v66, v80, v155
	v_add_f32_e32 v161, v97, v161
	v_exp_f32_e32 v191, v66
	v_sub_f32_e32 v66, v81, v155
	v_exp_f32_e32 v192, v66
	v_cvt_pk_bf16_f32 v66, v82, v83
	v_add_f32_e32 v82, v162, v161
	v_add_f32_e32 v82, v163, v82
	v_add_f32_e32 v82, v164, v82
	v_add_f32_e32 v82, v165, v82
	v_add_f32_e32 v82, v166, v82
	v_add_f32_e32 v82, v167, v82
	v_add_f32_e32 v82, v183, v82
	v_add_f32_e32 v82, v184, v82
	v_add_f32_e32 v82, v185, v82
	v_add_f32_e32 v82, v186, v82
	v_add_f32_e32 v82, v187, v82
	v_add_f32_e32 v82, v188, v82
	v_add_f32_e32 v82, v189, v82
	s_nop 4
	v_add_f32_e32 v82, v190, v82
	v_add_f32_e32 v82, v191, v82
	v_cvt_pk_bf16_f32 v67, v84, v85
	v_cvt_pk_bf16_f32 v68, v86, v87
	v_cvt_pk_bf16_f32 v69, v88, v89
	v_cvt_pk_bf16_f32 v70, v90, v91
	v_cvt_pk_bf16_f32 v71, v92, v93
	v_cvt_pk_bf16_f32 v72, v94, v95
	v_cvt_pk_bf16_f32 v73, v96, v97
	v_cvt_pk_bf16_f32 v74, v162, v163
	v_cvt_pk_bf16_f32 v75, v164, v165
	v_cvt_pk_bf16_f32 v76, v166, v167
	v_cvt_pk_bf16_f32 v77, v183, v184
	v_cvt_pk_bf16_f32 v78, v185, v186
	v_cvt_pk_bf16_f32 v79, v187, v188
	v_cvt_pk_bf16_f32 v80, v189, v190
	v_cvt_pk_bf16_f32 v81, v191, v192
	v_add_f32_e32 v86, v192, v82
	s_setprio 1
	v_add_u32_e32 v243, 0xb800, v242
	s_waitcnt lgkmcnt(0)
	ds_read2_b64 v[82:85], v243 offset0:96 offset1:98
	ds_read2_b64 v[90:93], v243 offset0:100 offset1:102
	ds_read2_b64 v[94:97], v243 offset0:104 offset1:106
	ds_read2_b64 v[162:165], v243 offset0:108 offset1:110
	v_add_f32_e32 v156, v156, v86
	v_mfma_f32_32x32x16_bf16 v[50:65], v[194:197], v[66:69], v[50:65]
	v_mfma_f32_32x32x16_bf16 v[50:65], v[198:201], v[70:73], v[50:65]
	v_mfma_f32_32x32x16_bf16 v[50:65], v[202:205], v[74:77], v[50:65]
	v_mfma_f32_32x32x16_bf16 v[50:65], v[206:209], v[78:81], v[50:65]
	v_mfma_f32_32x32x16_bf16 v[34:49], v[210:213], v[66:69], v[34:49]
	v_mfma_f32_32x32x16_bf16 v[34:49], v[214:217], v[70:73], v[34:49]
	v_mfma_f32_32x32x16_bf16 v[34:49], v[218:221], v[74:77], v[34:49]
	v_mfma_f32_32x32x16_bf16 v[34:49], v[222:225], v[78:81], v[34:49]
	v_mfma_f32_32x32x16_bf16 v[18:33], v[226:229], v[66:69], v[18:33]
	v_mfma_f32_32x32x16_bf16 v[18:33], v[230:233], v[70:73], v[18:33]
	v_mfma_f32_32x32x16_bf16 v[18:33], v[234:237], v[74:77], v[18:33]
	v_mfma_f32_32x32x16_bf16 v[18:33], v[238:241], v[78:81], v[18:33]
	s_waitcnt lgkmcnt(0)
	v_mfma_f32_32x32x16_bf16 v[2:17], v[82:85], v[66:69], v[2:17]
	v_mfma_f32_32x32x16_bf16 v[2:17], v[90:93], v[70:73], v[2:17]
	v_mfma_f32_32x32x16_bf16 v[2:17], v[94:97], v[74:77], v[2:17]
	v_mfma_f32_32x32x16_bf16 v[2:17], v[162:165], v[78:81], v[2:17]
	s_setprio 0
